# v18: P5 start staggered by workgroup group ((blockIdx>>3)&3)*~0.8us to de-synchronise the epilogue write bursts
# baseline (speedup 1.0000x reference)
.LBB0_1548:
	s_cmp_lt_i32 s92, 7
	s_cselect_b64 s[0:1], -1, 0
	s_and_b64 s[0:1], s[0:1], s[2:3]
	s_andn2_b64 vcc, exec, s[0:1]
	s_cbranch_vccnz .LBB0_1565
	s_cmpk_gt_i32 s85, 0x5d7
	v_readfirstlane_b32 s3, v1
	s_cbranch_scc1 .LBB0_1565
	s_bfe_u32 s59, s85, 0x20003
	s_cmp_eq_u32 s59, 0
	s_cbranch_scc1 .Lstg5_done
	s_sleep 28
	s_cmp_eq_u32 s59, 1
	s_cbranch_scc1 .Lstg5_done
	s_sleep 28
	s_cmp_eq_u32 s59, 2
	s_cbranch_scc1 .Lstg5_done
	s_sleep 28
.Lstg5_done:
	s_waitcnt vmcnt(0)
	v_lshrrev_b32_e32 v2, 5, v1
	v_lshrrev_b32_e32 v4, 1, v1
	v_and_b32_e32 v2, 4, v2
	s_waitcnt lgkmcnt(0)
	v_bfe_u32 v3, v1, 2, 2
	v_and_b32_e32 v13, 24, v4
	v_or3_b32 v2, v2, v3, v13
	v_lshlrev_b32_e32 v3, 4, v1
	v_add_u32_e32 v10, 0x2000, v3
	v_lshrrev_b32_e32 v4, 7, v10
	s_movk_i32 s2, 0xe0
	v_and_b32_e32 v6, 32, v1
	s_add_u32 s30, s46, 0xa00000
	v_and_or_b32 v5, v4, s2, v2
	v_bitop3_b32 v11, v3, v6, 48 bitop3:0x6c
	v_and_b32_e32 v12, 64, v1
	v_bfe_u32 v14, v1, 2, 4
	s_movk_i32 s2, 0xf0
	s_addc_u32 s31, s47, 0
	v_or_b32_e32 v3, v11, v12
	v_and_or_b32 v4, v4, s2, v14
	s_add_u32 s33, s46, 0x4f00000
	v_lshl_or_b32 v132, v4, 11, v3
	v_lshrrev_b32_e32 v4, 3, v1
	s_movk_i32 s2, 0x60
	s_addc_u32 s34, s47, 0
	v_and_or_b32 v2, v4, s2, v2
	s_movk_i32 s2, 0x70
	s_ashr_i32 s36, s85, 31
	v_lshl_or_b32 v134, v2, 11, v3
	v_and_or_b32 v2, v4, s2, v14
	s_lshr_b32 s2, s36, 29
	s_add_i32 s2, s85, s2
	s_lshr_b32 s10, s3, 6
	s_ashr_i32 s4, s2, 3
	s_and_b32 s2, s2, -8
	s_lshr_b32 s12, s3, 8
	s_lshl_b32 s35, s10, 10
	s_sub_i32 s2, s85, s2
	s_cmp_lt_i32 s2, 0
	s_movk_i32 s37, 0xbc
	s_cselect_b32 s5, s37, 0xbb
	s_mul_i32 s2, s2, s5
	s_add_i32 s2, s2, s4
	s_mul_hi_i32 s4, s2, 0x2e8ba2e9
	s_lshr_b32 s5, s4, 31
	s_ashr_i32 s4, s4, 5
	s_add_i32 s4, s4, s5
	s_lshl_b32 s6, s4, 3
	s_sub_i32 s5, 0x44, s6
	s_min_u32 s7, s5, 8
	s_mulk_i32 s4, 0xb0
	v_lshl_or_b32 v130, v5, 11, v3
	s_sub_i32 s8, s2, s4
	v_cvt_f32_ubyte0_e32 v5, s7
	v_cvt_f32_i32_e32 v4, s8
	v_rcp_iflag_f32_e32 v6, v5
	v_lshl_or_b32 v136, v2, 11, v3
	s_ashr_i32 s2, s8, 30
	s_or_b32 s2, s2, 1
	v_mul_f32_e32 v2, v4, v6
	v_trunc_f32_e32 v2, v2
	v_fma_f32 v3, -v2, v5, v4
	v_cvt_i32_f32_e32 v2, v2
	v_cmp_ge_f32_e64 s[4:5], |v3|, v5
	s_and_b64 s[4:5], s[4:5], exec
	s_cselect_b32 s2, s2, 0
	v_readfirstlane_b32 s4, v2
	s_add_i32 s2, s4, s2
	s_mul_i32 s4, s2, s7
	s_sub_i32 s4, s8, s4
	s_sext_i32_i16 s4, s4
	s_add_i32 s22, s6, s4
	s_ashr_i32 s23, s22, 31
	s_bfe_i64 s[6:7], s[2:3], 0x100000
	s_lshl_b64 s[4:5], s[22:23], 19
	s_lshl_b64 s[6:7], s[6:7], 19
	s_add_u32 s26, s30, s6
	s_addc_u32 s27, s31, s7
	s_add_i32 s23, s35, 0
	s_add_i32 m0, s23, 0x10000
	v_mov_b32_e32 v135, 0
	global_load_lds_dwordx4 v134, s[26:27]
	s_add_i32 m0, s23, 0x12000
	s_add_u32 s6, s26, 0x40000
	global_load_lds_dwordx4 v130, s[26:27]
	s_addc_u32 s7, s27, 0
	s_add_i32 m0, s23, 0x14000
	v_mov_b32_e32 v131, v135
	global_load_lds_dwordx4 v134, s[6:7]
	s_add_i32 m0, s23, 0x16000
	s_add_u32 s24, s33, s4
	s_addc_u32 s25, s34, s5
	s_add_i32 s38, s23, 0x2000
	global_load_lds_dwordx4 v130, s[6:7]
	s_mov_b32 m0, s23
	s_add_u32 s4, s24, 0x40000
	global_load_lds_dwordx4 v136, s[24:25]
	s_mov_b32 m0, s38
	s_addc_u32 s5, s25, 0
	s_add_i32 s39, s23, 0x4000
	global_load_lds_dwordx4 v132, s[24:25]
	s_mov_b32 m0, s39
	s_add_i32 s40, s23, 0x6000
	global_load_lds_dwordx4 v136, s[4:5]
	s_mov_b32 m0, s40
	v_mov_b32_e32 v137, v135
	global_load_lds_dwordx4 v132, s[4:5]
	v_mov_b32_e32 v133, v135
	s_cmp_eq_u32 s12, 1
	s_mov_b32 s41, 0
	v_lshl_add_u64 v[8:9], s[26:27], 0, v[134:135]
	v_lshl_add_u64 v[6:7], s[26:27], 0, v[130:131]
	v_lshl_add_u64 v[2:3], s[24:25], 0, v[136:137]
	s_cselect_b64 s[4:5], -1, 0
	s_cmp_lg_u32 s12, 1
	v_lshl_add_u64 v[4:5], s[24:25], 0, v[132:133]
	s_cbranch_scc1 .LBB0_1552
	s_barrier
